# P6 QH/VH loads via base+offset immediates; strips step-1 vmcnt counted for 2-tile prefetch
# baseline (speedup 1.0000x reference)
; #define LAS __attribute__((address_space(3)))
; __device__ __forceinline__ void sb_load(SbTile& t, const bf16* SK, const bf16* SV, int h, int kt, int lane) {
;     const bf16* kp = SK + (size_t)pos2row(kt + (lane & 31)) * 512 + h * 64 + 8 * (lane >> 5);
;     const bf16* vp = SV + (size_t)pos2row(kt + (lane >> 1)) * 512 + h * 64 + 32 * (lane & 1);
; #pragma unroll
;     for (int j = 0; j < 4; ++j) { t.k[j] = *(const bf16x8*)(kp + 16 * j); t.v[j] = *(const u32x4*)(vp + 8 * j); }
; }
; __device__ __forceinline__ void sb_strip(const bf16* SQ, const bf16* SK, const bf16* SV, bf16* OMIX, int h, int qpos0, int lane, LAS unsigned char* vl) {
;     const int l32 = lane & 31, hi = lane >> 5;
;     const int qrow = qpos0 - 128 + l32;
;     SbTile t0, t1, t2;
;     sb_load(t0, SK, SV, h, qpos0, lane); sb_load(t1, SK, SV, h, qpos0 - 32, lane);
;     bf16x8 qf[4];
;     { const bf16* qp = SQ + (size_t)qrow * 512 + h * 64 + 8 * hi;
; #pragma unroll
;       for (int j = 0; j < 4; ++j) qf[j] = *(const bf16x8*)(qp + 16 * j); }
;     f32x16 o0, o1;
; #pragma unroll
;     for (int r = 0; r < 16; ++r) { o0[r] = 0.f; o1[r] = 0.f; }
;     float carry = 0.f;
;     const int qpos = qpos0 + l32;
;     LAS unsigned char* vw = vl + (lane >> 1) * 144 + (lane & 1) * 64;
;     const LAS unsigned char* vr = vl + (4 * hi + ((lane & 15) >> 2)) * 144 + (16 * ((lane >> 4) & 1) + 4 * (lane & 3)) * 2;
.LBB0_1043:
	s_lshl_b32 s4, s28, 5
	s_and_b32 s6, s4, 0x3fe0
	s_add_i32 s4, s6, 0x80
	v_or_b32_e32 v202, s4, v181
	v_add_u32_e32 v0, 0xffffff80, v202
	s_ashr_i32 s4, s28, 3
	v_lshlrev_b64 v[2:3], 10, v[0:1]
	s_and_b32 s24, s4, 0xffffffc0
	v_or_b32_e32 v0, s6, v193
	s_ashr_i32 s25, s24, 31
	v_lshlrev_b32_e32 v0, 10, v0
	v_lshl_add_u64 v[2:3], s[20:21], 0, v[2:3]
	s_lshl_b64 s[4:5], s[24:25], 1
	v_lshl_add_u64 v[4:5], s[22:23], 0, v[0:1]
	v_or_b32_e32 v192, s6, v181
	v_lshl_add_u64 v[2:3], v[2:3], 0, s[4:5]
	v_lshl_add_u64 v[4:5], v[4:5], 0, s[4:5]
	s_addk_i32 s6, 0x60
	s_mul_i32 s100, s24, 0x8100
	v_lshlrev_b32_e32 v222, 4, v201
	v_add_u32_e32 v222, s100, v222
	v_mov_b32_e32 v223, 0
	v_lshl_add_u64 v[218:219], s[20:21], 0, v[222:223]
	v_lshl_add_u64 v[230:231], s[22:23], 0, v[222:223]
	v_mov_b32_e32 v222, s6
	v_lshlrev_b32_e32 v222, 7, v222
	v_lshl_add_u64 v[226:227], v[218:219], 0, v[222:223]
	v_lshl_add_u64 v[234:235], v[230:231], 0, v[222:223]
	v_add_u32_e32 v222, 0x1000, v222
	v_lshl_add_u64 v[224:225], v[218:219], 0, v[222:223]
	v_lshl_add_u64 v[232:233], v[230:231], 0, v[222:223]
	s_and_b32 s46, s30, 0x3fe0
	v_lshl_add_u64 v[2:3], v[2:3], 0, v[186:187]
	v_lshl_add_u64 v[4:5], v[4:5], 0, v[188:189]
	v_or_b32_e32 v0, s6, v181
	global_load_dwordx4 v[118:121], v[232:233], off offset:3072
	global_load_dwordx4 v[126:129], v[232:233], off offset:2048
	global_load_dwordx4 v[130:133], v[232:233], off offset:1024
	global_load_dwordx4 v[134:137], v[232:233], off
	global_load_dwordx4 v[90:93], v[224:225], off
	global_load_dwordx4 v[94:97], v[224:225], off offset:1024
	global_load_dwordx4 v[86:89], v[224:225], off offset:2048
	global_load_dwordx4 v[82:85], v[224:225], off offset:3072
	s_cmpk_gt_u32 s6, 0x7f
	v_add_u32_e32 v2, 0xffffff80, v0
	v_max_u32_e32 v0, 0x70, v0
	v_add_u32_e32 v0, 0x3f90, v0
	s_cselect_b64 vcc, -1, 0
	v_cndmask_b32_e32 v0, v0, v2, vcc
	v_lshlrev_b64 v[2:3], 10, v[0:1]
	v_or_b32_e32 v0, s6, v193
	v_add_u32_e32 v4, 0xffffff80, v0
	v_max_u32_e32 v0, 0x70, v0
	v_add_u32_e32 v0, 0x3f90, v0
	v_cndmask_b32_e32 v0, v0, v4, vcc
	v_lshlrev_b64 v[4:5], 10, v[0:1]
	v_lshl_add_u64 v[4:5], s[22:23], 0, v[4:5]
	v_lshl_add_u64 v[2:3], s[20:21], 0, v[2:3]
	v_lshl_add_u64 v[4:5], v[4:5], 0, s[4:5]
	v_lshl_add_u64 v[2:3], v[2:3], 0, s[4:5]
	v_lshl_add_u64 v[4:5], v[4:5], 0, v[188:189]
	v_readlane_b32 s6, v237, 35
	v_lshl_add_u64 v[2:3], v[2:3], 0, v[186:187]
	global_load_dwordx4 v[146:149], v[234:235], off offset:3072
	global_load_dwordx4 v[150:153], v[234:235], off offset:2048
	global_load_dwordx4 v[154:157], v[234:235], off offset:1024
	global_load_dwordx4 v[158:161], v[234:235], off
	global_load_dwordx4 v[102:105], v[226:227], off
	global_load_dwordx4 v[110:113], v[226:227], off offset:1024
	global_load_dwordx4 v[106:109], v[226:227], off offset:2048
	global_load_dwordx4 v[98:101], v[226:227], off offset:3072
	v_lshlrev_b32_e32 v0, 10, v192
	v_readlane_b32 s7, v237, 36
	v_mov_b32_e32 v14, v1
	v_mov_b32_e32 v15, v1
	v_lshl_add_u64 v[2:3], s[6:7], 0, v[0:1]
	v_lshl_add_u64 v[2:3], v[2:3], 0, s[4:5]
	v_lshl_add_u64 v[2:3], v[2:3], 0, v[190:191]
	global_load_dwordx4 v[66:69], v[2:3], off
	global_load_dwordx4 v[70:73], v[2:3], off offset:32
	global_load_dwordx4 v[74:77], v[2:3], off offset:64
	global_load_dwordx4 v[78:81], v[2:3], off offset:96
	v_mov_b32_e32 v0, v1
	v_mov_b32_e32 v2, v1
	v_mov_b32_e32 v3, v1
	v_mov_b32_e32 v4, v1
	v_mov_b32_e32 v5, v1
	v_mov_b32_e32 v6, v1
	v_mov_b32_e32 v7, v1
	v_mov_b32_e32 v8, v1
	v_mov_b32_e32 v9, v1
	v_mov_b32_e32 v10, v1
	v_mov_b32_e32 v11, v1
	v_mov_b32_e32 v12, v1
	v_mov_b32_e32 v13, v1
	v_mov_b64_e32 v[32:33], v[14:15]
	v_mov_b64_e32 v[30:31], v[12:13]
	v_mov_b64_e32 v[28:29], v[10:11]
	v_mov_b64_e32 v[26:27], v[8:9]
	v_mov_b64_e32 v[24:25], v[6:7]
	v_mov_b64_e32 v[22:23], v[4:5]
	v_mov_b64_e32 v[20:21], v[2:3]
	v_mov_b64_e32 v[18:19], v[0:1]
	v_mov_b64_e32 v[16:17], v[14:15]
	v_or_b32_e32 v203, s46, v193
	v_or_b32_e32 v204, s46, v181
	v_or_b32_e32 v205, s46, v180
	v_lshl_add_u64 v[194:195], v[182:183], 0, s[4:5]
	v_lshl_add_u64 v[196:197], v[184:185], 0, s[4:5]
	s_mov_b32 s47, 0
	v_mov_b32_e32 v208, v1
	v_mov_b64_e32 v[14:15], v[12:13]
	v_mov_b64_e32 v[12:13], v[10:11]
	v_mov_b64_e32 v[10:11], v[8:9]
	v_mov_b64_e32 v[8:9], v[6:7]
	v_mov_b64_e32 v[6:7], v[4:5]
	v_mov_b64_e32 v[4:5], v[2:3]
	v_mov_b64_e32 v[2:3], v[0:1]
	s_waitcnt vmcnt(0)
	s_branch .LBB0_1046

; #define LAS __attribute__((address_space(3)))
; __device__ __forceinline__ int crow(int r, int hi) { return (r & 3) + 8 * (r >> 2) + 4 * hi; }
; #define MFMA32(a, b, c) __builtin_amdgcn_mfma_f32_32x32x16_bf16((a), (b), (c), 0, 0, 0)
; __device__ __forceinline__ void sb_load(SbTile& t, const bf16* SK, const bf16* SV, int h, int kt, int lane) {
;     const bf16* kp = SK + (size_t)pos2row(kt + (lane & 31)) * 512 + h * 64 + 8 * (lane >> 5);
;     const bf16* vp = SV + (size_t)pos2row(kt + (lane >> 1)) * 512 + h * 64 + 32 * (lane & 1);
; #pragma unroll
;     for (int j = 0; j < 4; ++j) { t.k[j] = *(const bf16x8*)(kp + 16 * j); t.v[j] = *(const u32x4*)(vp + 8 * j); }
; }
; template <bool MASK> __device__ __forceinline__ void sb_tile(const SbTile& t0, const bf16x8 (&qf)[4], f32x16& o0, f32x16& o1, float& carry, int kt, int qpos, int hi, LAS unsigned char* vw, const LAS unsigned char* vr) {
; #pragma unroll
;     for (int j = 0; j < 4; ++j) *(LAS u32x4*)(vw + 16 * j) = t0.v[j];
;     f32x16 z;
; #pragma unroll
;     for (int r = 0; r < 16; ++r) z[r] = 0.f;
; #pragma unroll
;     for (int j = 0; j < 4; ++j) z = MFMA32(t0.k[j], qf[j], z);
;     float kp[16], bt[16];
; #pragma unroll
;     for (int r = 0; r < 16; ++r) { const float e = __builtin_amdgcn_exp2f(z[r]); const float k = __builtin_amdgcn_rcpf(1.0f + e); const float b = e * k;
;         if (MASK) { const int kpos = kt + crow(r, hi); const bool okr = (kpos < qpos) && (kpos >= 112); kp[r] = okr ? k : 1.0f; bt[r] = okr ? b : 0.f; } else { kp[r] = k; bt[r] = b; } }
.LBB0_1046:
	s_add_i32 s49, s46, s47
	v_add_u32_e32 v206, s47, v204
	s_add_i32 s48, s49, 64
	v_add_u32_e32 v0, 64, v206
	s_cmpk_gt_u32 s48, 0x7f
	v_max_u32_e32 v0, 0x70, v0
	v_subrev_u32_e32 v34, 64, v206
	v_add_u32_e32 v0, 0x3f90, v0
	s_cselect_b64 vcc, -1, 0
	v_cndmask_b32_e32 v0, v0, v34, vcc
	v_add_u32_e32 v207, s47, v203
	v_lshlrev_b64 v[34:35], 10, v[0:1]
	v_add_u32_e32 v0, 64, v207
	v_max_u32_e32 v0, 0x70, v0
	v_subrev_u32_e32 v36, 64, v207
	v_add_u32_e32 v0, 0x3f90, v0
	v_cndmask_b32_e32 v0, v0, v36, vcc
	v_lshlrev_b64 v[36:37], 10, v[0:1]
	v_lshl_add_u64 v[36:37], v[196:197], 0, v[36:37]
	v_lshl_add_u64 v[34:35], v[194:195], 0, v[34:35]
	v_mov_b32_e32 v222, s48
	v_lshlrev_b32_e32 v222, 7, v222
	v_mov_b32_e32 v223, 0
	v_lshl_add_u64 v[220:221], v[218:219], 0, v[222:223]
	v_lshl_add_u64 v[228:229], v[230:231], 0, v[222:223]
	global_load_dwordx4 v[162:165], v[228:229], off offset:3072
	global_load_dwordx4 v[166:169], v[228:229], off offset:2048
	global_load_dwordx4 v[170:173], v[228:229], off offset:1024
	global_load_dwordx4 v[174:177], v[228:229], off
	global_load_dwordx4 v[142:145], v[220:221], off
	global_load_dwordx4 v[138:141], v[220:221], off offset:1024
	global_load_dwordx4 v[122:125], v[220:221], off offset:2048
	global_load_dwordx4 v[114:117], v[220:221], off offset:3072
	v_add_co_u32_e64 v0, s[6:7], s49, v198
	s_nop 0
	v_readfirstlane_b32 s50, v0
	s_cmp_eq_u32 s47, 0
	v_exp_f32_e64 v0, -v208
	s_cselect_b64 s[4:5], -1, 0
	s_or_b64 s[4:5], s[4:5], s[6:7]
	s_andn2_b64 vcc, exec, s[4:5]
	s_mov_b64 s[4:5], -1
	s_waitcnt vmcnt(20)
	ds_write_b128 v199, v[134:137]
	ds_write_b128 v199, v[130:133] offset:16
	ds_write_b128 v199, v[126:129] offset:32
	ds_write_b128 v199, v[118:121] offset:48
	s_cbranch_vccz .LBB0_1048
	s_waitcnt vmcnt(19)
	v_mfma_f32_32x32x16_bf16 v[34:49], v[90:93], v[66:69], 0
	s_mov_b64 s[4:5], 0
	s_waitcnt vmcnt(18)
	v_mfma_f32_32x32x16_bf16 v[34:49], v[94:97], v[70:73], v[34:49]
	s_waitcnt vmcnt(17)
	v_mfma_f32_32x32x16_bf16 v[34:49], v[86:89], v[74:77], v[34:49]
	s_waitcnt vmcnt(16)
	v_mfma_f32_32x32x16_bf16 v[34:49], v[82:85], v[78:81], v[34:49]
	s_nop 11
	v_exp_f32_e32 v39, v39
	v_exp_f32_e32 v40, v40
	v_exp_f32_e32 v41, v41
	v_exp_f32_e32 v42, v42
	v_exp_f32_e32 v44, v44
	v_exp_f32_e32 v45, v45
	v_exp_f32_e32 v62, v46
	v_add_f32_e32 v55, 1.0, v39
	v_add_f32_e32 v57, 1.0, v40
	v_add_f32_e32 v58, 1.0, v41
	v_add_f32_e32 v59, 1.0, v42
	v_add_f32_e32 v61, 1.0, v44
	v_add_f32_e32 v46, 1.0, v45
	v_rcp_f32_e32 v56, v55
	v_rcp_f32_e32 v55, v57
	v_rcp_f32_e32 v57, v58
	v_rcp_f32_e32 v58, v59
	v_rcp_f32_e32 v59, v61
	v_rcp_f32_e32 v61, v46
	v_exp_f32_e32 v63, v47
	v_add_f32_e32 v46, 1.0, v62
	v_rcp_f32_e32 v64, v46
	v_exp_f32_e32 v46, v48
	v_exp_f32_e32 v47, v49
	v_exp_f32_e32 v43, v43
	v_add_f32_e32 v48, 1.0, v63
	v_exp_f32_e32 v38, v38
	v_rcp_f32_e32 v130, v48
	v_add_f32_e32 v48, 1.0, v46
	v_rcp_f32_e32 v65, v48
	v_add_f32_e32 v48, 1.0, v47
	v_add_f32_e32 v60, 1.0, v43
	v_rcp_f32_e32 v131, v48
	v_rcp_f32_e32 v60, v60
	v_add_f32_e32 v54, 1.0, v38
	v_and_b32_e32 v49, 64, v201
	v_exp_f32_e32 v36, v36
	v_exp_f32_e32 v37, v37
	v_rcp_f32_e32 v54, v54
	v_xor_b32_e32 v48, 32, v201
	v_add_u32_e32 v49, 64, v49
	v_exp_f32_e32 v34, v34
	v_exp_f32_e32 v35, v35
	v_cmp_lt_i32_e32 vcc, v48, v49
	v_pk_mul_f32 v[118:119], v[64:65], v[130:131]
	v_add_f32_e32 v52, 1.0, v36
	v_cndmask_b32_e32 v48, v201, v48, vcc
	v_mul_f32_e32 v120, v118, v119
	v_pk_mul_f32 v[118:119], v[58:59], v[60:61]
	v_lshlrev_b32_e32 v126, 2, v48
	v_mul_f32_e32 v118, v118, v119
	v_add_f32_e32 v53, 1.0, v37
	v_pk_mul_f32 v[48:49], v[54:55], v[56:57]
	ds_bpermute_b32 v121, v126, v120
	ds_bpermute_b32 v127, v126, v118
	v_add_f32_e32 v50, 1.0, v34
	v_add_f32_e32 v51, 1.0, v35
	v_rcp_f32_e32 v52, v52
	v_rcp_f32_e32 v53, v53
	v_pk_mul_f32 v[48:49], v[48:49], v[48:49] op_sel:[0,1] op_sel_hi:[1,0]
	v_rcp_f32_e32 v50, v50
	v_rcp_f32_e32 v51, v51
	ds_bpermute_b32 v49, v126, v48
	s_waitcnt lgkmcnt(2)
	v_cndmask_b32_e64 v128, 1.0, v121, s[0:1]
	v_mul_f32_e32 v119, v120, v121
	s_waitcnt lgkmcnt(1)
	v_mul_f32_e32 v121, v118, v127
	v_mov_b32_e32 v118, v52
	v_mov_b32_e32 v120, v53
	v_mul_f32_e32 v129, v0, v119
	v_pk_mul_f32 v[118:119], v[118:119], v[120:121]
	v_mov_b32_e32 v120, v50
	v_mov_b32_e32 v121, v48
	v_mov_b32_e32 v48, v51
	v_cndmask_b32_e64 v132, 1.0, v127, s[0:1]
	s_waitcnt lgkmcnt(0)
	v_cndmask_b32_e64 v127, 1.0, v49, s[0:1]
	v_pk_mul_f32 v[48:49], v[120:121], v[48:49]
	v_pk_mul_f32 v[36:37], v[36:37], v[52:53]
	v_pk_mul_f32 v[210:211], v[48:49], v[118:119]
	ds_bpermute_b32 v209, v126, v210
	v_mul_f32_e32 v48, v0, v211
	v_pk_mul_f32 v[34:35], v[34:35], v[50:51]
	v_mul_f32_e32 v118, v0, v119
	v_mov_b32_e32 v50, v54
	s_waitcnt lgkmcnt(0)
	v_cndmask_b32_e64 v49, 1.0, v209, s[0:1]
	v_mul_f32_e32 v49, v49, v48
	v_mul_f32_e32 v48, v53, v49
	v_pk_mul_f32 v[36:37], v[36:37], v[48:49]
	v_mul_f32_e32 v49, v52, v48
	v_mul_f32_e32 v48, v51, v49
	v_pk_mul_f32 v[34:35], v[34:35], v[48:49]
	v_mov_b32_e32 v48, v55
	v_mov_b32_e32 v49, v57
	v_pk_mul_f32 v[40:41], v[40:41], v[48:49]
	v_mul_f32_e32 v49, v127, v118
	v_mul_f32_e32 v48, v57, v49
	v_pk_mul_f32 v[40:41], v[40:41], v[48:49]
	v_mov_b32_e32 v51, v56
	v_mul_f32_e32 v49, v55, v48
	v_pk_mul_f32 v[38:39], v[38:39], v[50:51]
	v_mul_f32_e32 v48, v56, v49
	v_pk_mul_f32 v[38:39], v[38:39], v[48:49]
	v_mov_b32_e32 v48, v59
	v_mov_b32_e32 v49, v61
	v_pk_mul_f32 v[44:45], v[44:45], v[48:49]
	v_mul_f32_e32 v49, v132, v129
	v_mul_f32_e32 v48, v61, v49
	v_pk_mul_f32 v[134:135], v[44:45], v[48:49]
	v_mov_b32_e32 v44, v58
	v_mov_b32_e32 v45, v60
	ds_read_b64_tr_b16 v[50:51], v200
	ds_read_b64_tr_b16 v[52:53], v200 offset:1152
	v_pk_mul_f32 v[42:43], v[42:43], v[44:45]
	v_mul_f32_e32 v45, v59, v48
	v_mul_f32_e32 v55, v0, v128
	ds_read_b64_tr_b16 v[128:129], v200 offset:1216
	ds_read_b64_tr_b16 v[126:127], v200 offset:64
	v_mul_f32_e32 v44, v60, v45
	v_pk_mul_f32 v[136:137], v[42:43], v[44:45]
	v_mov_b32_e32 v42, v65
	v_mov_b32_e32 v43, v131
	v_pk_mul_f32 v[42:43], v[46:47], v[42:43]
	v_mul_f32_e32 v54, v131, v55
	v_cvt_pk_bf16_f32 v118, v34, v35
	v_cvt_pk_bf16_f32 v119, v36, v37
	v_cvt_pk_bf16_f32 v120, v38, v39
	v_cvt_pk_bf16_f32 v121, v40, v41
	v_pk_mul_f32 v[212:213], v[42:43], v[54:55]
	v_mul_f32_e32 v217, v65, v54
	s_waitcnt lgkmcnt(2)
; #define LAS __attribute__((address_space(3)))
; __device__ __forceinline__ unsigned cvtpk_s(float lo, float hi) { f32x2_t v = {lo, hi}; bf16x2_t b = __builtin_convertvector(v, bf16x2_t); return __builtin_bit_cast(unsigned, b); }
; template <bool MASK> __device__ __forceinline__ void sb_tile(const SbTile& t0, const bf16x8 (&qf)[4], f32x16& o0, f32x16& o1, float& carry, int kt, int qpos, int hi, LAS unsigned char* vw, const LAS unsigned char* vr) {
; #pragma unroll
;     for (int j = 0; j < 4; ++j) *(LAS u32x4*)(vw + 16 * j) = t0.v[j];
;     f32x16 z;
; #pragma unroll
;     for (int r = 0; r < 16; ++r) z[r] = 0.f;
; #pragma unroll
;     for (int j = 0; j < 4; ++j) z = MFMA32(t0.k[j], qf[j], z);
;     float kp[16], bt[16];
; #pragma unroll
;     for (int r = 0; r < 16; ++r) { const float e = __builtin_amdgcn_exp2f(z[r]); const float k = __builtin_amdgcn_rcpf(1.0f + e); const float b = e * k;
;         if (MASK) { const int kpos = kt + crow(r, hi); const bool okr = (kpos < qpos) && (kpos >= 112); kp[r] = okr ? k : 1.0f; bt[r] = okr ? b : 0.f; } else { kp[r] = k; bt[r] = b; } }
;     float G[4], Go[4];
; #pragma unroll
;     for (int g = 0; g < 4; ++g) { G[g] = (kp[4 * g] * kp[4 * g + 1]) * (kp[4 * g + 2] * kp[4 * g + 3]); Go[g] = __shfl_xor(G[g], 32); }
;     const float c0 = __builtin_amdgcn_exp2f(-carry);
;     float offs[4]; float T = 1.0f;
; #pragma unroll
;     for (int g = 3; g >= 0; --g) { offs[g] = c0 * T * (hi == 0 ? Go[g] : 1.0f); T *= G[g] * Go[g]; }
;     f32x16 w;
; #pragma unroll
;     for (int g = 0; g < 4; ++g) { float run = offs[g];
; #pragma unroll
;         for (int i = 3; i >= 0; --i) { const int r = 4 * g + i; w[r] = bt[r] * run; run *= kp[r]; } }
;     carry -= __builtin_amdgcn_logf(T);
; #pragma unroll
;     for (int s = 0; s < 2; ++s) { u32x4 wp;
; #pragma unroll
;         for (int i = 0; i < 4; ++i) wp[i] = cvtpk_s(w[8 * s + 2 * i], w[8 * s + 2 * i + 1]);
;         const bf16x8 wb = __builtin_bit_cast(bf16x8, wp);
;         const s16x4 a0 = vtr(vr + (16 * s) * 144), a1 = vtr(vr + (16 * s + 8) * 144), b0 = vtr(vr + (16 * s) * 144 + 64), b1 = vtr(vr + (16 * s + 8) * 144 + 64);
;         const bf16x8 v0 = __builtin_shufflevector(a0, a1, 0, 1, 2, 3, 4, 5, 6, 7), v1 = __builtin_shufflevector(b0, b1, 0, 1, 2, 3, 4, 5, 6, 7);
;         o0 = MFMA32(v0, wb, o0); o1 = MFMA32(v1, wb, o1); }
	v_mfma_f32_32x32x16_bf16 v[34:49], v[50:53], v[118:121], v[2:17]
	v_mov_b32_e32 v50, v64
	v_mov_b32_e32 v51, v130
	v_mul_f32_e64 v214, v62, v50
	v_mul_f32_e64 v215, v63, v51
	v_mul_f32_e32 v216, v130, v217
	ds_read_b64_tr_b16 v[130:131], v200 offset:2304
	ds_read_b64_tr_b16 v[132:133], v200 offset:3456
	s_waitcnt lgkmcnt(2)
	v_mfma_f32_32x32x16_bf16 v[50:65], v[126:129], v[118:121], v[18:33]
	v_cvt_pk_bf16_f32 v126, v136, v137
	v_cvt_pk_bf16_f32 v127, v134, v135
	ds_read_b64_tr_b16 v[136:137], v200 offset:3520
	ds_read_b64_tr_b16 v[134:135], v200 offset:2368
	v_mul_f32_e64 v118, v214, v216
	v_mul_f32_e64 v119, v215, v217
	v_cvt_pk_bf16_f32 v129, v212, v213
	v_cvt_pk_bf16_f32 v128, v118, v119
	v_mul_f32_e32 v118, v210, v209
	v_mul_f32_e32 v118, v118, v211
	s_waitcnt lgkmcnt(2)
	v_mfma_f32_32x32x16_bf16 v[34:49], v[130:133], v[126:129], v[34:49]
	v_log_f32_e32 v118, v118
	s_waitcnt lgkmcnt(0)
	v_mfma_f32_32x32x16_bf16 v[50:65], v[134:137], v[126:129], v[50:65]
.LBB0_1048:
	s_andn2_b64 vcc, exec, s[4:5]
	s_cbranch_vccnz .LBB0_1050
	s_waitcnt vmcnt(19)
	v_mfma_f32_32x32x16_bf16 v[34:49], v[90:93], v[66:69], 0
	s_nop 7
	v_add_u32_e32 v51, s47, v205
	v_add_u32_e32 v50, 0x81, v51
	v_cmp_lt_u32_e64 s[4:5], v50, v202
	v_add_u32_e32 v50, 0x82, v51
	v_cmp_lt_u32_e64 s[10:11], v50, v202
	v_add_u32_e32 v50, 0x83, v51
	v_cmp_lt_u32_e64 s[14:15], v50, v202
	s_waitcnt vmcnt(18)
	v_mfma_f32_32x32x16_bf16 v[34:49], v[94:97], v[70:73], v[34:49]
	v_add_u32_e32 v52, 0x80, v51
	s_cmpk_gt_u32 s50, 0x6f
	s_cselect_b64 s[16:17], -1, 0
	v_cmp_lt_u32_e32 vcc, v52, v202
	v_cmp_lt_u32_e64 s[8:9], s34, v52
	v_cmp_lt_u32_e64 s[12:13], s35, v52
	s_and_b64 vcc, s[16:17], vcc
	s_waitcnt vmcnt(17)
	v_mfma_f32_32x32x16_bf16 v[34:49], v[86:89], v[74:77], v[34:49]
	s_and_b64 s[4:5], s[8:9], s[4:5]
	s_and_b64 s[8:9], s[12:13], s[10:11]
	s_waitcnt vmcnt(16)
	v_mfma_f32_32x32x16_bf16 v[34:49], v[82:85], v[78:81], v[34:49]
	s_nop 11
	v_exp_f32_e32 v34, v34
	v_exp_f32_e32 v35, v35
	v_exp_f32_e32 v50, v36
	v_exp_f32_e32 v53, v38
	v_add_f32_e32 v36, 1.0, v34
	v_add_f32_e32 v38, 1.0, v35
	v_exp_f32_e32 v37, v37
	v_add_f32_e32 v54, 1.0, v50
	v_rcp_f32_e32 v36, v36
	v_rcp_f32_e32 v38, v38
	v_rcp_f32_e32 v54, v54
	v_add_f32_e32 v55, 1.0, v37
	v_mul_f32_e32 v56, v34, v36
	v_mul_f32_e32 v35, v35, v38
	v_rcp_f32_e32 v55, v55
	v_cndmask_b32_e32 v34, 1.0, v36, vcc
	v_cndmask_b32_e64 v36, 1.0, v38, s[4:5]
	v_mul_f32_e32 v50, v50, v54
	v_cndmask_b32_e64 v38, 1.0, v54, s[8:9]
	v_cndmask_b32_e32 v54, 0, v56, vcc
	v_cndmask_b32_e64 v56, 0, v35, s[4:5]
	v_add_f32_e32 v35, 1.0, v53
	v_rcp_f32_e32 v35, v35
	v_exp_f32_e32 v39, v39
	v_cmp_lt_u32_e32 vcc, s36, v52
	v_mul_f32_e32 v37, v37, v55
	s_and_b64 vcc, vcc, s[14:15]
	v_cndmask_b32_e64 v57, 0, v50, s[8:9]
	v_cndmask_b32_e32 v50, 1.0, v55, vcc
	v_cndmask_b32_e32 v55, 0, v37, vcc
	v_mul_f32_e32 v37, v53, v35
	v_add_u32_e32 v53, 0x88, v51
	v_cmp_lt_u32_e32 vcc, v53, v202
	v_add_f32_e32 v53, 1.0, v39
	v_rcp_f32_e32 v53, v53
	s_cmpk_gt_u32 s50, 0x67
	s_cselect_b64 s[4:5], -1, 0
	s_and_b64 vcc, s[4:5], vcc
	v_cndmask_b32_e32 v58, 0, v37, vcc
	v_mul_f32_e32 v37, v39, v53
	v_exp_f32_e32 v39, v40
	v_add_u32_e32 v40, 0x89, v51
	v_cndmask_b32_e32 v35, 1.0, v35, vcc
	v_cmp_lt_u32_e32 vcc, v40, v202
	v_add_f32_e32 v40, 1.0, v39
	v_rcp_f32_e32 v40, v40
	v_cmp_lt_u32_e64 s[4:5], s38, v52
	s_and_b64 vcc, s[4:5], vcc
	v_cndmask_b32_e32 v59, 0, v37, vcc
	v_mul_f32_e32 v37, v39, v40
	v_exp_f32_e32 v39, v41
	v_add_u32_e32 v41, 0x8a, v51
	v_cndmask_b32_e32 v53, 1.0, v53, vcc
	v_cmp_lt_u32_e32 vcc, v41, v202
	v_add_f32_e32 v41, 1.0, v39
	v_rcp_f32_e32 v41, v41
	v_cmp_lt_u32_e64 s[4:5], s39, v52
	s_and_b64 vcc, s[4:5], vcc
	v_cndmask_b32_e32 v61, 0, v37, vcc
	v_mul_f32_e32 v37, v39, v41
	v_exp_f32_e32 v39, v42
	v_cndmask_b32_e32 v60, 1.0, v40, vcc
	v_add_u32_e32 v40, 0x8b, v51
	v_cmp_lt_u32_e32 vcc, v40, v202
	v_cmp_lt_u32_e64 s[4:5], s44, v52
	s_and_b64 vcc, s[4:5], vcc
	v_add_f32_e32 v40, 1.0, v39
	v_cndmask_b32_e32 v42, 1.0, v41, vcc
	v_exp_f32_e32 v41, v43
	v_rcp_f32_e32 v40, v40
	v_cndmask_b32_e32 v43, 0, v37, vcc
	v_mul_f32_e32 v35, v35, v53
	v_add_f32_e32 v52, 1.0, v41
	v_mul_f32_e32 v37, v39, v40
	v_add_u32_e32 v39, 0x90, v51
	v_rcp_f32_e32 v52, v52
	v_cmp_lt_u32_e32 vcc, v39, v202
	s_nop 1
	v_cndmask_b32_e32 v39, 1.0, v40, vcc
	v_exp_f32_e32 v40, v44
	v_cndmask_b32_e32 v44, 0, v37, vcc
	v_mul_f32_e32 v37, v41, v52
	v_add_u32_e32 v41, 0x91, v51
	v_cmp_lt_u32_e32 vcc, v41, v202
	v_exp_f32_e32 v41, v45
	v_add_f32_e32 v62, 1.0, v40
	v_rcp_f32_e32 v62, v62
	v_cndmask_b32_e32 v45, 0, v37, vcc
	v_add_f32_e32 v63, 1.0, v41
	v_rcp_f32_e32 v63, v63
	v_mul_f32_e32 v37, v40, v62
	v_add_u32_e32 v40, 0x92, v51
	v_cndmask_b32_e32 v52, 1.0, v52, vcc
	v_cmp_lt_u32_e32 vcc, v40, v202
	v_exp_f32_e32 v40, v46
	v_mul_f32_e32 v39, v39, v52
	v_cndmask_b32_e32 v64, 0, v37, vcc
	v_mul_f32_e32 v37, v41, v63
	v_add_u32_e32 v41, 0x93, v51
	v_cndmask_b32_e32 v62, 1.0, v62, vcc
	v_cmp_lt_u32_e32 vcc, v41, v202
	v_exp_f32_e32 v41, v47
	v_add_f32_e32 v46, 1.0, v40
	v_rcp_f32_e32 v46, v46
	v_cndmask_b32_e32 v65, 0, v37, vcc
	v_add_f32_e32 v47, 1.0, v41
	v_rcp_f32_e32 v47, v47
	v_mul_f32_e32 v37, v40, v46
	v_add_u32_e32 v40, 0x98, v51
	v_cndmask_b32_e32 v63, 1.0, v63, vcc
	v_cmp_lt_u32_e32 vcc, v40, v202
	s_nop 1
	v_cndmask_b32_e32 v40, 1.0, v46, vcc
	v_exp_f32_e32 v46, v48
	v_cndmask_b32_e32 v48, 0, v37, vcc
	v_mul_f32_e32 v37, v41, v47
	v_add_u32_e32 v41, 0x99, v51
	v_cmp_lt_u32_e32 vcc, v41, v202
	v_exp_f32_e32 v41, v49
	v_add_f32_e32 v82, 1.0, v46
	v_rcp_f32_e32 v82, v82
	v_cndmask_b32_e32 v83, 1.0, v47, vcc
	v_add_f32_e32 v47, 1.0, v41
	v_rcp_f32_e32 v47, v47
	v_cndmask_b32_e32 v49, 0, v37, vcc
	v_mul_f32_e32 v37, v46, v82
	v_add_u32_e32 v46, 0x9a, v51
	v_cmp_lt_u32_e32 vcc, v46, v202
	v_mul_f32_e32 v40, v40, v83
	v_mul_f32_e32 v46, v62, v63
	v_cndmask_b32_e32 v84, 0, v37, vcc
	v_mul_f32_e32 v37, v41, v47
	v_add_u32_e32 v41, 0x9b, v51
	v_cndmask_b32_e32 v82, 1.0, v82, vcc
	v_cmp_lt_u32_e32 vcc, v41, v202
	v_and_b32_e32 v41, 64, v201
	v_add_u32_e32 v41, 64, v41
	v_cndmask_b32_e32 v86, 0, v37, vcc
	v_xor_b32_e32 v37, 32, v201
	v_cndmask_b32_e32 v85, 1.0, v47, vcc
	v_cmp_lt_i32_e32 vcc, v37, v41
	v_mul_f32_e32 v41, v82, v85
	v_mul_f32_e32 v40, v40, v41
	v_cndmask_b32_e32 v37, v201, v37, vcc
	v_lshlrev_b32_e32 v87, 2, v37
	ds_bpermute_b32 v41, v87, v40
	v_mul_f32_e32 v37, v60, v42
	v_mul_f32_e32 v46, v39, v46
	v_mul_f32_e32 v35, v35, v37
	ds_bpermute_b32 v47, v87, v46
	ds_bpermute_b32 v37, v87, v35
	s_waitcnt lgkmcnt(2)
; __device__ __forceinline__ unsigned cvtpk_s(float lo, float hi) { f32x2_t v = {lo, hi}; bf16x2_t b = __builtin_convertvector(v, bf16x2_t); return __builtin_bit_cast(unsigned, b); }
; #define MFMA32(a, b, c) __builtin_amdgcn_mfma_f32_32x32x16_bf16((a), (b), (c), 0, 0, 0)
; __device__ __forceinline__ s16x4 vtr(const LAS unsigned char* p) { return __builtin_bit_cast(s16x4, __builtin_amdgcn_ds_read_tr16_b64_v4i16((LAS s16x4*)p)); }
; template <bool MASK> __device__ __forceinline__ void sb_tile(const SbTile& t0, const bf16x8 (&qf)[4], f32x16& o0, f32x16& o1, float& carry, int kt, int qpos, int hi, LAS unsigned char* vw, const LAS unsigned char* vr) {
;     ...
;     float G[4], Go[4];
; #pragma unroll
;     for (int g = 0; g < 4; ++g) { G[g] = (kp[4 * g] * kp[4 * g + 1]) * (kp[4 * g + 2] * kp[4 * g + 3]); Go[g] = __shfl_xor(G[g], 32); }
;     const float c0 = __builtin_amdgcn_exp2f(-carry);
;     float offs[4]; float T = 1.0f;
; #pragma unroll
;     for (int g = 3; g >= 0; --g) { offs[g] = c0 * T * (hi == 0 ? Go[g] : 1.0f); T *= G[g] * Go[g]; }
;     f32x16 w;
; #pragma unroll
;     for (int g = 0; g < 4; ++g) { float run = offs[g];
; #pragma unroll
;         for (int i = 3; i >= 0; --i) { const int r = 4 * g + i; w[r] = bt[r] * run; run *= kp[r]; } }
;     carry -= __builtin_amdgcn_logf(T);
; #pragma unroll
;     for (int s = 0; s < 2; ++s) { u32x4 wp;
; #pragma unroll
;         for (int i = 0; i < 4; ++i) wp[i] = cvtpk_s(w[8 * s + 2 * i], w[8 * s + 2 * i + 1]);
;         const bf16x8 wb = __builtin_bit_cast(bf16x8, wp);
;         const s16x4 a0 = vtr(vr + (16 * s) * 144), a1 = vtr(vr + (16 * s + 8) * 144), b0 = vtr(vr + (16 * s) * 144 + 64), b1 = vtr(vr + (16 * s + 8) * 144 + 64);
;         const bf16x8 v0 = __builtin_shufflevector(a0, a1, 0, 1, 2, 3, 4, 5, 6, 7), v1 = __builtin_shufflevector(b0, b1, 0, 1, 2, 3, 4, 5, 6, 7);
;         o0 = MFMA32(v0, wb, o0); o1 = MFMA32(v1, wb, o1); }
	v_cndmask_b32_e64 v39, 1.0, v41, s[0:1]
	v_mul_f32_e32 v88, v0, v39
	v_mul_f32_e32 v39, v40, v41
	v_mul_f32_e32 v40, v0, v39
	s_waitcnt lgkmcnt(1)
	v_cndmask_b32_e64 v41, 1.0, v47, s[0:1]
	v_mul_f32_e32 v51, v46, v47
	v_mul_f32_e32 v89, v41, v40
	v_pk_mul_f32 v[40:41], v[38:39], v[50:51]
	s_waitcnt lgkmcnt(0)
	v_pk_mul_f32 v[34:35], v[34:35], v[36:37]
	s_nop 0
	v_pk_mul_f32 v[46:47], v[34:35], v[40:41]
	ds_bpermute_b32 v51, v87, v46
	v_cndmask_b32_e64 v34, 1.0, v37, s[0:1]
	v_mul_f32_e32 v35, v0, v41
	v_mul_f32_e32 v34, v34, v35
	v_mul_f32_e32 v0, v0, v47
	s_waitcnt lgkmcnt(0)
	v_cndmask_b32_e64 v35, 1.0, v51, s[0:1]
	v_mul_f32_e32 v0, v35, v0
	v_mul_f32_e32 v41, v43, v34
	v_mul_f32_e32 v34, v42, v34
	v_mul_f32_e32 v39, v55, v0
	v_mul_f32_e32 v0, v50, v0
	v_mul_f32_e32 v42, v61, v34
	v_mul_f32_e32 v34, v60, v34
	v_mul_f32_e32 v40, v57, v0
	v_mul_f32_e32 v0, v38, v0
	v_mul_f32_e32 v43, v59, v34
	v_mul_f32_e32 v34, v53, v34
	v_mul_f32_e32 v38, v56, v0
	v_mul_f32_e32 v0, v36, v0
	v_mul_f32_e32 v50, v58, v34
	v_mul_f32_e32 v34, v63, v89
	v_mul_f32_e32 v0, v54, v0
	v_mul_f32_e32 v54, v64, v34
	v_mul_f32_e32 v34, v62, v34
	v_mul_f32_e32 v55, v45, v34
	v_mul_f32_e32 v45, v52, v34
	ds_read_b64_tr_b16 v[34:35], v200
	ds_read_b64_tr_b16 v[36:37], v200 offset:1152
	v_mul_f32_e32 v52, v44, v45
	v_cvt_pk_bf16_f32 v39, v40, v39
	v_cvt_pk_bf16_f32 v40, v50, v43
	v_cvt_pk_bf16_f32 v41, v42, v41
	ds_read_b64_tr_b16 v[44:45], v200 offset:1216
	ds_read_b64_tr_b16 v[42:43], v200 offset:64
	v_cvt_pk_bf16_f32 v38, v0, v38
	v_mul_f32_e32 v0, v85, v88
	v_mul_f32_e32 v50, v84, v0
	s_waitcnt lgkmcnt(2)
	v_mfma_f32_32x32x16_bf16 v[2:17], v[34:37], v[38:41], v[2:17]
	ds_read_b64_tr_b16 v[34:35], v200 offset:2304
	ds_read_b64_tr_b16 v[36:37], v200 offset:3456
	v_mul_f32_e32 v0, v82, v0
	v_mul_f32_e32 v49, v49, v0
	v_mul_f32_e32 v0, v83, v0
	v_mul_f32_e32 v53, v65, v89
	v_mul_f32_e32 v56, v86, v88
	v_mul_f32_e32 v0, v48, v0
	s_waitcnt lgkmcnt(2)
	v_mfma_f32_32x32x16_bf16 v[18:33], v[42:45], v[38:41], v[18:33]
	ds_read_b64_tr_b16 v[44:45], v200 offset:3520
	ds_read_b64_tr_b16 v[42:43], v200 offset:2368
	v_cvt_pk_bf16_f32 v38, v52, v55
	v_cvt_pk_bf16_f32 v39, v54, v53
	v_cvt_pk_bf16_f32 v40, v0, v49
	v_cvt_pk_bf16_f32 v41, v50, v56
	v_mul_f32_e32 v0, v46, v51
	v_mul_f32_e32 v0, v0, v47
	s_waitcnt lgkmcnt(2)
	v_mfma_f32_32x32x16_bf16 v[2:17], v[34:37], v[38:41], v[2:17]
	v_log_f32_e32 v118, v0
	s_waitcnt lgkmcnt(0)
	v_mfma_f32_32x32x16_bf16 v[18:33], v[42:45], v[38:41], v[18:33]
	s_nop 8
	v_mov_b64_e32 v[48:49], v[16:17]
	v_mov_b64_e32 v[46:47], v[14:15]
	v_mov_b64_e32 v[44:45], v[12:13]
	v_mov_b64_e32 v[42:43], v[10:11]
	v_mov_b64_e32 v[40:41], v[8:9]
	v_mov_b64_e32 v[38:39], v[6:7]
	v_mov_b64_e32 v[36:37], v[4:5]
	v_mov_b64_e32 v[64:65], v[32:33]
	v_mov_b64_e32 v[62:63], v[30:31]
	v_mov_b64_e32 v[60:61], v[28:29]
	v_mov_b64_e32 v[58:59], v[26:27]
	v_mov_b64_e32 v[56:57], v[24:25]
	v_mov_b64_e32 v[54:55], v[22:23]
	v_mov_b64_e32 v[52:53], v[20:21]
	v_mov_b64_e32 v[50:51], v[18:19]
	v_mov_b64_e32 v[34:35], v[2:3]
